# mixer co-located role split: in each of the two passes all 8 waves of a workgroup work on the same 128-row chunk (4 pooling waves + 4 gating waves; gating item swapped between wave halves) so whole pr
# baseline (speedup 1.0000x reference)
; #define LAS __attribute__((address_space(3)))
; #define LDS_WAIT() asm volatile("s_waitcnt lgkmcnt(0)" ::: "memory")
; __device__ __forceinline__ void sgu_item(LAS unsigned char* wl, const bf16* proj, bf16* ymix, const float* vstat, const float* sgu_g, const bf16* Wm, const float* sgu_b, int chunk, int h, int lane) {
;     proj += (size_t)(chunk >> 6) * GAP_P; ymix += (size_t)(chunk >> 6) * GAP_Y;
;     typedef float f32x2 __attribute__((ext_vector_type(2)));
;     const size_t R0 = (size_t)chunk * 128;
;     const int r = lane & 15, q = lane >> 4, c16 = lane & 3, rsub = lane >> 2;
;     LAS f32x2* st = (LAS f32x2*)(wl + 128 * VP2);
; #pragma unroll
;     for (int hh = 0; hh < 2; ++hh) { const f32x4* sp = (const f32x4*)(vstat + (R0 + lane + 64 * hh) * 16);
;         const f32x4 a = sp[0], b = sp[1], c = sp[2], d = sp[3];
;         const float s1 = ((a[0] + a[2]) + (b[0] + b[2])) + ((c[0] + c[2]) + (d[0] + d[2])), s2 = ((a[1] + a[3]) + (b[1] + b[3])) + ((c[1] + c[3]) + (d[1] + d[3]));
;         const float mean = s1 * (1.0f / 512.0f), var = fmaxf(s2 * (1.0f / 512.0f) - mean * mean, 0.f);
;         st[lane + 64 * hh] = (f32x2){mean, __builtin_amdgcn_rsqf(var + EPS)}; }
;     bf16x8 wmf[20];
;     { const bf16* wm = Wm + (size_t)(h * 128 + r) * 128 + q * 8; int f = 0;
; #pragma unroll
;       for (int ks = 0; ks < 4; ++ks)
; #pragma unroll
;         for (int tb = 2 * ks; tb < 8; ++tb) wmf[f++] = *(const bf16x8*)(wm + (size_t)(16 * tb) * 128 + ks * 32); }
;     float bias[8];
; #pragma unroll
;     for (int tb = 0; tb < 8; ++tb) bias[tb] = sgu_b[h * 128 + 16 * tb + r];
;     LDS_WAIT();
; __device__ __forceinline__ void mixer_phase(LAS unsigned char* lds, const bf16* proj, bf16* ymix, const float* vstat, const bf16* WpT, const float* pscale, const float* sgu_g, const bf16* Wm, const float* sgu_b, int pool_first, int pool_step, int pool_limit, int sgu_first, int sgu_step, int sgu_limi ...
;     int tid = tid_in; asm volatile("" : "+v"(tid));
;     const int lane = tid & 63, wave = __builtin_amdgcn_readfirstlane(tid >> 6);
;     LAS unsigned char* wl = lds + wave * MIXW;
;     { v4u raw[12]; if (pool_first < pool_limit) pool_load(proj, pool_first, lane, raw);
;       for (int it = pool_first; it < pool_limit; it += pool_step) pool_item(wl, proj, ymix, WpT, pscale, it >> 4, (it >> 2) & 3, it & 3, lane, raw, it + pool_step < pool_limit ? it + pool_step : -1); }
.LBB0_508:
	v_readlane_b32 s0, v254, 50
	v_readlane_b32 s1, v254, 51
	s_andn2_b64 vcc, exec, s[0:1]
	s_cbranch_vccnz .LBB0_513
	s_cmp_lg_u32 s98, 0
	s_cbranch_scc1 .LBB0_513
	v_readlane_b32 s22, v255, 37
	s_lshl_b32 s86, s22, 9
	v_readlane_b32 s4, v253, 3
	s_lshl_b64 s[0:1], s[86:87], 2
	v_readlane_b32 s14, v253, 13
	v_readlane_b32 s5, v253, 4
	v_readlane_b32 s15, v253, 14
	s_add_u32 s14, s4, s0
	s_waitcnt vmcnt(0)
	v_lshrrev_b32_e32 v0, 1, v81
	v_readlane_b32 s18, v253, 17
	s_addc_u32 s15, s5, s1
	v_and_b32_e32 v2, 24, v0
	v_readlane_b32 s0, v255, 39
	v_readlane_b32 s19, v253, 18
	s_add_u32 s18, s38, 0x25100000
	v_lshlrev_b32_e32 v192, 1, v2
	v_readlane_b32 s1, v255, 40
	s_addc_u32 s19, s39, 0
	v_or_b32_e32 v7, 0x70, v140
	v_lshl_add_u64 v[0:1], s[0:1], 0, v[192:193]
	s_mov_b64 s[0:1], 0x1e40000
	v_lshl_add_u64 v[144:145], v[0:1], 0, s[0:1]
	s_add_u32 s0, s20, 0x10900400
	v_and_b32_e32 v8, 48, v81
	v_and_b32_e32 v143, 15, v81
	v_and_b32_e32 v0, 24, v83
	s_addc_u32 s1, s21, 0
	v_lshl_or_b32 v192, v7, 11, v8
	v_add_u32_e32 v4, s2, v0
	v_bfe_u32 v0, v81, 2, 2
	v_or_b32_e32 v6, 48, v140
	v_lshl_add_u64 v[146:147], s[0:1], 0, v[192:193]
	v_lshl_or_b32 v192, v143, 11, v8
	v_or_b32_e32 v0, v0, v2
	v_lshl_add_u64 v[148:149], s[20:21], 0, v[192:193]
	v_lshl_or_b32 v192, v6, 11, v8
	v_mul_u32_u24_e32 v2, 0x50, v0
	v_lshl_add_u64 v[150:151], s[0:1], 0, v[192:193]
	s_add_u32 s0, s26, 0xf100400
	v_mul_u32_u24_e32 v0, 0xc00, v7
	s_addc_u32 s1, s27, 0
	v_mul_hi_u32_u24_e32 v1, 0xc00, v7
	v_or_b32_e32 v0, v0, v8
	v_lshl_add_u64 v[152:153], s[0:1], 0, v[0:1]
	v_mul_u32_u24_e32 v0, 0xc00, v143
	v_mul_hi_u32_u24_e32 v1, 0xc00, v143
	v_or_b32_e32 v0, v0, v8
	v_lshl_add_u64 v[154:155], s[26:27], 0, v[0:1]
	v_mul_u32_u24_e32 v0, 0xc00, v6
	v_readlane_b32 s23, v255, 38
	v_lshrrev_b32_e32 v3, 2, v140
	v_mul_hi_u32_u24_e32 v1, 0xc00, v6
	v_or_b32_e32 v0, v0, v8
	v_add_u32_e32 v141, s2, v83
	v_lshl_add_u32 v218, v3, 3, s2
	v_lshl_add_u64 v[156:157], s[0:1], 0, v[0:1]
	s_lshl_b64 s[0:1], s[22:23], 11
	v_readlane_b32 s2, v255, 14
	v_mul_u32_u24_e32 v5, 0x50, v3
	v_mul_hi_u32_u24_e32 v1, 0xc00, v3
	v_mul_u32_u24_e32 v0, 0xc00, v3
	v_and_b32_e32 v3, 3, v81
	s_add_u32 s0, s2, s0
	v_readlane_b32 s2, v255, 15
	v_readlane_b32 s7, v253, 6
	v_lshl_or_b32 v0, v3, 4, v0
	v_lshlrev_b32_e32 v192, 5, v3
	s_addc_u32 s1, s2, s1
	v_or_b32_e32 v142, 64, v140
	v_lshl_add_u64 v[158:159], s[26:27], 0, v[0:1]
	v_lshl_add_u64 v[160:161], s[0:1], 0, v[192:193]
	v_add_u32_e32 v219, v4, v5
	v_add_u32_e32 v220, v4, v2
	v_readlane_b32 s4, v254, 62
	v_readlane_b32 s5, v254, 61
	v_readlane_b32 s2, v254, 49
	v_readlane_b32 s7, v254, 63
	v_readlane_b32 s6, v253, 5
	v_readlane_b32 s8, v253, 7
	v_readlane_b32 s9, v253, 8
	v_readlane_b32 s10, v253, 9
	v_readlane_b32 s11, v253, 10
	v_readlane_b32 s12, v253, 11
	v_readlane_b32 s13, v253, 12
	v_readlane_b32 s16, v253, 15
	v_readlane_b32 s17, v253, 16
	s_xor_b32 s5, s5, 4
	s_xor_b32 s4, s4, 0x200
	s_add_i32 s2, s5, 1
